# GEMM k-loops Ph4/Ph5/Ph6: the load-free MFMA slots of the even step moved one MFMA earlier (after MFMAs 2,6,10,14)
# speedup vs baseline: 1.0029x; 1.0012x over previous
.Lg4_noraise:
.Lg4_loop:
	v_add_u32_e32 v190, s40, v186
	v_add_u32_e32 v191, s40, v187
	v_add_u32_e32 v250, s40, v188
	v_add_u32_e32 v251, s40, v189
	ds_read_b128 v[200:203], v190
	ds_read_b128 v[204:207], v190 offset:2048
	ds_read_b128 v[222:225], v250
	ds_read_b128 v[226:229], v250 offset:2048
	ds_read_b128 v[230:233], v250 offset:4096
	ds_read_b128 v[234:237], v250 offset:6144
	s_waitcnt lgkmcnt(3)
	v_mfma_f32_32x32x16_bf16 v[112:127], v[200:203], v[222:225], v[112:127]
	global_load_dwordx4 v[128:131], v176, s[28:29]
	ds_read_b128 v[208:211], v191
	v_mfma_f32_32x32x16_bf16 v[48:63], v[204:207], v[222:225], v[48:63]
	global_load_dwordx4 v[132:135], v177, s[28:29]
	ds_read_b128 v[212:215], v191 offset:2048
	s_waitcnt lgkmcnt(4)
	v_mfma_f32_32x32x16_bf16 v[96:111], v[200:203], v[226:229], v[96:111]
	ds_read_b128 v[238:241], v251
	v_mfma_f32_32x32x16_bf16 v[32:47], v[204:207], v[226:229], v[32:47]
	global_load_dwordx4 v[136:139], v178, s[28:29]
	ds_read_b128 v[242:245], v251 offset:2048
	s_waitcnt lgkmcnt(5)
	v_mfma_f32_32x32x16_bf16 v[80:95], v[200:203], v[230:233], v[80:95]
	global_load_dwordx4 v[140:143], v179, s[28:29]
	ds_read_b128 v[246:249], v251 offset:4096
	v_mfma_f32_32x32x16_bf16 v[16:31], v[204:207], v[230:233], v[16:31]
	global_load_dwordx4 v[144:147], v176, s[38:39]
	ds_read_b128 v[192:195], v251 offset:6144
	s_waitcnt lgkmcnt(6)
	v_mfma_f32_32x32x16_bf16 v[64:79], v[200:203], v[234:237], v[64:79]
	v_mfma_f32_32x32x16_bf16 v[0:15], v[204:207], v[234:237], v[0:15]
	global_load_dwordx4 v[148:151], v177, s[38:39]
	v_xad_u32 v190, v186, 64, s41
	v_xad_u32 v250, v188, 64, s41
	s_waitcnt lgkmcnt(3)
	v_mfma_f32_32x32x16_bf16 v[112:127], v[208:211], v[238:241], v[112:127]
	global_load_dwordx4 v[152:155], v178, s[38:39]
	ds_read_b128 v[200:203], v190
	v_mfma_f32_32x32x16_bf16 v[48:63], v[212:215], v[238:241], v[48:63]
	global_load_dwordx4 v[156:159], v179, s[38:39]
	ds_read_b128 v[204:207], v190 offset:2048
	s_waitcnt lgkmcnt(4)
	v_mfma_f32_32x32x16_bf16 v[96:111], v[208:211], v[242:245], v[96:111]
	ds_read_b128 v[222:225], v250
	v_mfma_f32_32x32x16_bf16 v[32:47], v[212:215], v[242:245], v[32:47]
	global_load_dwordx4 v[160:163], v180, s[38:39]
	ds_read_b128 v[226:229], v250 offset:2048
	s_waitcnt lgkmcnt(5)
	v_mfma_f32_32x32x16_bf16 v[80:95], v[208:211], v[246:249], v[80:95]
	global_load_dwordx4 v[164:167], v181, s[38:39]
	ds_read_b128 v[230:233], v250 offset:4096
	v_mfma_f32_32x32x16_bf16 v[16:31], v[212:215], v[246:249], v[16:31]
	global_load_dwordx4 v[168:171], v182, s[38:39]
	ds_read_b128 v[234:237], v250 offset:6144
	s_waitcnt lgkmcnt(6)
	v_mfma_f32_32x32x16_bf16 v[64:79], v[208:211], v[192:195], v[64:79]
	v_mfma_f32_32x32x16_bf16 v[0:15], v[212:215], v[192:195], v[0:15]
	global_load_dwordx4 v[172:175], v184, s[38:39]
	s_barrier
	v_xad_u32 v191, v187, 64, s41
	v_xad_u32 v251, v189, 64, s41
	s_waitcnt lgkmcnt(3)
	v_mfma_f32_32x32x16_bf16 v[112:127], v[200:203], v[222:225], v[112:127]
	ds_read_b128 v[208:211], v191
	v_mfma_f32_32x32x16_bf16 v[48:63], v[204:207], v[222:225], v[48:63]
	ds_read_b128 v[212:215], v191 offset:2048
	s_waitcnt lgkmcnt(4)
	v_mfma_f32_32x32x16_bf16 v[96:111], v[200:203], v[226:229], v[96:111]
	ds_read_b128 v[238:241], v251
	s_waitcnt vmcnt(11)
	ds_write_b128 v185, v[128:131]
	v_mfma_f32_32x32x16_bf16 v[32:47], v[204:207], v[226:229], v[32:47]
	ds_read_b128 v[242:245], v251 offset:2048
	s_waitcnt vmcnt(10)
	ds_write_b128 v185, v[132:135] offset:2048
	s_waitcnt lgkmcnt(7)
	v_mfma_f32_32x32x16_bf16 v[80:95], v[200:203], v[230:233], v[80:95]
	ds_read_b128 v[246:249], v251 offset:4096
	s_waitcnt vmcnt(9)
	ds_write_b128 v185, v[136:139] offset:4096
	v_mfma_f32_32x32x16_bf16 v[16:31], v[204:207], v[230:233], v[16:31]
	ds_read_b128 v[192:195], v251 offset:6144
	s_waitcnt vmcnt(8)
	ds_write_b128 v185, v[140:143] offset:6144
	s_waitcnt lgkmcnt(10)
	v_mfma_f32_32x32x16_bf16 v[64:79], v[200:203], v[234:237], v[64:79]
	s_waitcnt vmcnt(7)
	ds_write_b128 v185, v[144:147] offset:8192
	v_mfma_f32_32x32x16_bf16 v[0:15], v[204:207], v[234:237], v[0:15]
	s_waitcnt vmcnt(6)
	ds_write_b128 v185, v[148:151] offset:10240
	s_waitcnt lgkmcnt(9)
	v_mfma_f32_32x32x16_bf16 v[112:127], v[208:211], v[238:241], v[112:127]
	s_waitcnt vmcnt(5)
	ds_write_b128 v185, v[152:155] offset:12288
	v_mfma_f32_32x32x16_bf16 v[48:63], v[212:215], v[238:241], v[48:63]
	s_waitcnt vmcnt(4)
	ds_write_b128 v185, v[156:159] offset:14336
	s_waitcnt lgkmcnt(9)
	v_mfma_f32_32x32x16_bf16 v[96:111], v[208:211], v[242:245], v[96:111]
	s_waitcnt vmcnt(3)
	ds_write_b128 v185, v[160:163] offset:16384
	v_mfma_f32_32x32x16_bf16 v[32:47], v[212:215], v[242:245], v[32:47]
	s_waitcnt vmcnt(2)
	ds_write_b128 v185, v[164:167] offset:18432
	s_waitcnt lgkmcnt(9)
	v_mfma_f32_32x32x16_bf16 v[80:95], v[208:211], v[246:249], v[80:95]
	s_waitcnt vmcnt(1)
	ds_write_b128 v185, v[168:171] offset:20480
	v_mfma_f32_32x32x16_bf16 v[16:31], v[212:215], v[246:249], v[16:31]
	s_waitcnt vmcnt(0)
	ds_write_b128 v185, v[172:175] offset:22528
	s_waitcnt lgkmcnt(9)
	v_mfma_f32_32x32x16_bf16 v[64:79], v[208:211], v[192:195], v[64:79]
	v_mfma_f32_32x32x16_bf16 v[0:15], v[212:215], v[192:195], v[0:15]
	s_add_u32 s28, s28, 0x80
	s_addc_u32 s29, s29, 0
	s_add_u32 s38, s38, 0x80
	s_addc_u32 s39, s39, 0
	s_sub_i32 s40, s40, 0x6000
	s_cmp_lt_i32 s40, 0
	s_cselect_b32 s42, 0x12000, 0
	s_add_i32 s40, s40, s42
	s_sub_i32 s41, s41, 0x6000
	s_cmp_lt_i32 s41, 0
	s_cselect_b32 s42, 0x12000, 0
	s_add_i32 s41, s41, s42
	v_subrev_u32_e32 v196, 0x6000, v185
	v_add_u32_e32 v198, 0xc000, v185
	v_min_u32_e32 v185, v196, v198
	s_add_i32 s7, s7, 1
	s_cmp_lt_u32 s7, 15
	s_waitcnt lgkmcnt(0)
	s_barrier
	s_cbranch_scc1 .Lg4_loop
	v_add_u32_e32 v190, s40, v186
	v_add_u32_e32 v191, s40, v187
	v_add_u32_e32 v250, s40, v188
	v_add_u32_e32 v251, s40, v189
	ds_read_b128 v[200:203], v190
	ds_read_b128 v[204:207], v190 offset:2048
	ds_read_b128 v[222:225], v250
	ds_read_b128 v[226:229], v250 offset:2048
	ds_read_b128 v[230:233], v250 offset:4096
	ds_read_b128 v[234:237], v250 offset:6144
	s_waitcnt lgkmcnt(3)
	v_mfma_f32_32x32x16_bf16 v[112:127], v[200:203], v[222:225], v[112:127]
	ds_read_b128 v[208:211], v191
	v_mfma_f32_32x32x16_bf16 v[48:63], v[204:207], v[222:225], v[48:63]
	ds_read_b128 v[212:215], v191 offset:2048
	s_waitcnt lgkmcnt(4)
	v_mfma_f32_32x32x16_bf16 v[96:111], v[200:203], v[226:229], v[96:111]
	ds_read_b128 v[238:241], v251
	v_mfma_f32_32x32x16_bf16 v[32:47], v[204:207], v[226:229], v[32:47]
	ds_read_b128 v[242:245], v251 offset:2048
	s_waitcnt lgkmcnt(5)
	v_mfma_f32_32x32x16_bf16 v[80:95], v[200:203], v[230:233], v[80:95]
	ds_read_b128 v[246:249], v251 offset:4096
	v_mfma_f32_32x32x16_bf16 v[16:31], v[204:207], v[230:233], v[16:31]
	ds_read_b128 v[192:195], v251 offset:6144
	s_waitcnt lgkmcnt(6)
	v_mfma_f32_32x32x16_bf16 v[64:79], v[200:203], v[234:237], v[64:79]
	v_mfma_f32_32x32x16_bf16 v[0:15], v[204:207], v[234:237], v[0:15]
	v_xad_u32 v190, v186, 64, s41
	v_xad_u32 v250, v188, 64, s41
	s_waitcnt lgkmcnt(3)
	v_mfma_f32_32x32x16_bf16 v[112:127], v[208:211], v[238:241], v[112:127]
	ds_read_b128 v[200:203], v190
	v_mfma_f32_32x32x16_bf16 v[48:63], v[212:215], v[238:241], v[48:63]
	ds_read_b128 v[204:207], v190 offset:2048
	s_waitcnt lgkmcnt(4)
	v_mfma_f32_32x32x16_bf16 v[96:111], v[208:211], v[242:245], v[96:111]
	ds_read_b128 v[222:225], v250
	v_mfma_f32_32x32x16_bf16 v[32:47], v[212:215], v[242:245], v[32:47]
	ds_read_b128 v[226:229], v250 offset:2048
	s_waitcnt lgkmcnt(5)
	v_mfma_f32_32x32x16_bf16 v[80:95], v[208:211], v[246:249], v[80:95]
	ds_read_b128 v[230:233], v250 offset:4096
	v_mfma_f32_32x32x16_bf16 v[16:31], v[212:215], v[246:249], v[16:31]
	ds_read_b128 v[234:237], v250 offset:6144
	s_waitcnt lgkmcnt(6)
	v_mfma_f32_32x32x16_bf16 v[64:79], v[208:211], v[192:195], v[64:79]
	v_mfma_f32_32x32x16_bf16 v[0:15], v[212:215], v[192:195], v[0:15]
	v_xad_u32 v191, v187, 64, s41
	v_xad_u32 v251, v189, 64, s41
	s_waitcnt lgkmcnt(3)
	v_mfma_f32_32x32x16_bf16 v[112:127], v[200:203], v[222:225], v[112:127]
	ds_read_b128 v[208:211], v191
	v_mfma_f32_32x32x16_bf16 v[48:63], v[204:207], v[222:225], v[48:63]
	ds_read_b128 v[212:215], v191 offset:2048
	s_waitcnt lgkmcnt(4)
	v_mfma_f32_32x32x16_bf16 v[96:111], v[200:203], v[226:229], v[96:111]
	ds_read_b128 v[238:241], v251
	v_mfma_f32_32x32x16_bf16 v[32:47], v[204:207], v[226:229], v[32:47]
	ds_read_b128 v[242:245], v251 offset:2048
	s_waitcnt lgkmcnt(5)
	v_mfma_f32_32x32x16_bf16 v[80:95], v[200:203], v[230:233], v[80:95]
	ds_read_b128 v[246:249], v251 offset:4096
	v_mfma_f32_32x32x16_bf16 v[16:31], v[204:207], v[230:233], v[16:31]
	ds_read_b128 v[192:195], v251 offset:6144
	s_waitcnt lgkmcnt(6)
	v_mfma_f32_32x32x16_bf16 v[64:79], v[200:203], v[234:237], v[64:79]
	v_mfma_f32_32x32x16_bf16 v[0:15], v[204:207], v[234:237], v[0:15]
	s_waitcnt lgkmcnt(3)
	v_mfma_f32_32x32x16_bf16 v[112:127], v[208:211], v[238:241], v[112:127]
	v_mfma_f32_32x32x16_bf16 v[48:63], v[212:215], v[238:241], v[48:63]
	s_waitcnt lgkmcnt(2)
	v_mfma_f32_32x32x16_bf16 v[96:111], v[208:211], v[242:245], v[96:111]
	v_mfma_f32_32x32x16_bf16 v[32:47], v[212:215], v[242:245], v[32:47]
	s_waitcnt lgkmcnt(1)
	v_mfma_f32_32x32x16_bf16 v[80:95], v[208:211], v[246:249], v[80:95]
	v_mfma_f32_32x32x16_bf16 v[16:31], v[212:215], v[246:249], v[16:31]
	s_waitcnt lgkmcnt(0)
	v_mfma_f32_32x32x16_bf16 v[64:79], v[208:211], v[192:195], v[64:79]
	v_mfma_f32_32x32x16_bf16 v[0:15], v[212:215], v[192:195], v[0:15]
	s_setprio 0
	s_nop 7
	s_nop 7

.Lg5_noraise:
.Lg5_loop:
	v_add_u32_e32 v190, s36, v186
	v_add_u32_e32 v191, s36, v187
	v_add_u32_e32 v250, s36, v188
	v_add_u32_e32 v251, s36, v189
	ds_read_b128 v[200:203], v190
	ds_read_b128 v[204:207], v190 offset:2048
	ds_read_b128 v[222:225], v250
	ds_read_b128 v[226:229], v250 offset:2048
	ds_read_b128 v[230:233], v250 offset:4096
	ds_read_b128 v[234:237], v250 offset:6144
	s_waitcnt lgkmcnt(3)
	v_mfma_f32_32x32x16_bf16 v[112:127], v[200:203], v[222:225], v[112:127]
	global_load_dwordx4 v[128:131], v178, s[42:43]
	ds_read_b128 v[208:211], v191
	v_mfma_f32_32x32x16_bf16 v[48:63], v[204:207], v[222:225], v[48:63]
	global_load_dwordx4 v[132:135], v179, s[42:43]
	ds_read_b128 v[212:215], v191 offset:2048
	s_waitcnt lgkmcnt(4)
	v_mfma_f32_32x32x16_bf16 v[96:111], v[200:203], v[226:229], v[96:111]
	ds_read_b128 v[238:241], v251
	v_mfma_f32_32x32x16_bf16 v[32:47], v[204:207], v[226:229], v[32:47]
	global_load_dwordx4 v[136:139], v180, s[42:43]
	ds_read_b128 v[242:245], v251 offset:2048
	s_waitcnt lgkmcnt(5)
	v_mfma_f32_32x32x16_bf16 v[80:95], v[200:203], v[230:233], v[80:95]
	global_load_dwordx4 v[140:143], v181, s[42:43]
	ds_read_b128 v[246:249], v251 offset:4096
	v_mfma_f32_32x32x16_bf16 v[16:31], v[204:207], v[230:233], v[16:31]
	global_load_dwordx4 v[144:147], v178, s[44:45]
	ds_read_b128 v[192:195], v251 offset:6144
	s_waitcnt lgkmcnt(6)
	v_mfma_f32_32x32x16_bf16 v[64:79], v[200:203], v[234:237], v[64:79]
	v_mfma_f32_32x32x16_bf16 v[0:15], v[204:207], v[234:237], v[0:15]
	global_load_dwordx4 v[148:151], v179, s[44:45]
	v_xad_u32 v190, v186, 64, s37
	v_xad_u32 v250, v188, 64, s37
	s_waitcnt lgkmcnt(3)
	v_mfma_f32_32x32x16_bf16 v[112:127], v[208:211], v[238:241], v[112:127]
	global_load_dwordx4 v[152:155], v180, s[44:45]
	ds_read_b128 v[200:203], v190
	v_mfma_f32_32x32x16_bf16 v[48:63], v[212:215], v[238:241], v[48:63]
	global_load_dwordx4 v[156:159], v181, s[44:45]
	ds_read_b128 v[204:207], v190 offset:2048
	s_waitcnt lgkmcnt(4)
	v_mfma_f32_32x32x16_bf16 v[96:111], v[208:211], v[242:245], v[96:111]
	ds_read_b128 v[222:225], v250
	v_mfma_f32_32x32x16_bf16 v[32:47], v[212:215], v[242:245], v[32:47]
	global_load_dwordx4 v[160:163], v182, s[44:45]
	ds_read_b128 v[226:229], v250 offset:2048
	s_waitcnt lgkmcnt(5)
	v_mfma_f32_32x32x16_bf16 v[80:95], v[208:211], v[246:249], v[80:95]
	global_load_dwordx4 v[164:167], v183, s[44:45]
	ds_read_b128 v[230:233], v250 offset:4096
	v_mfma_f32_32x32x16_bf16 v[16:31], v[212:215], v[246:249], v[16:31]
	global_load_dwordx4 v[168:171], v184, s[44:45]
	ds_read_b128 v[234:237], v250 offset:6144
	s_waitcnt lgkmcnt(6)
	v_mfma_f32_32x32x16_bf16 v[64:79], v[208:211], v[192:195], v[64:79]
	v_mfma_f32_32x32x16_bf16 v[0:15], v[212:215], v[192:195], v[0:15]
	global_load_dwordx4 v[172:175], v185, s[44:45]
	s_barrier
	v_xad_u32 v191, v187, 64, s37
	v_xad_u32 v251, v189, 64, s37
	s_waitcnt lgkmcnt(3)
	v_mfma_f32_32x32x16_bf16 v[112:127], v[200:203], v[222:225], v[112:127]
	ds_read_b128 v[208:211], v191
	v_mfma_f32_32x32x16_bf16 v[48:63], v[204:207], v[222:225], v[48:63]
	ds_read_b128 v[212:215], v191 offset:2048
	s_waitcnt lgkmcnt(4)
	v_mfma_f32_32x32x16_bf16 v[96:111], v[200:203], v[226:229], v[96:111]
	ds_read_b128 v[238:241], v251
	s_waitcnt vmcnt(11)
	ds_write_b128 v177, v[128:131]
	v_mfma_f32_32x32x16_bf16 v[32:47], v[204:207], v[226:229], v[32:47]
	ds_read_b128 v[242:245], v251 offset:2048
	s_waitcnt vmcnt(10)
	ds_write_b128 v177, v[132:135] offset:2048
	s_waitcnt lgkmcnt(7)
	v_mfma_f32_32x32x16_bf16 v[80:95], v[200:203], v[230:233], v[80:95]
	ds_read_b128 v[246:249], v251 offset:4096
	s_waitcnt vmcnt(9)
	ds_write_b128 v177, v[136:139] offset:4096
	v_mfma_f32_32x32x16_bf16 v[16:31], v[204:207], v[230:233], v[16:31]
	ds_read_b128 v[192:195], v251 offset:6144
	s_waitcnt vmcnt(8)
	ds_write_b128 v177, v[140:143] offset:6144
	s_waitcnt lgkmcnt(10)
	v_mfma_f32_32x32x16_bf16 v[64:79], v[200:203], v[234:237], v[64:79]
	s_waitcnt vmcnt(7)
	ds_write_b128 v177, v[144:147] offset:8192
	v_mfma_f32_32x32x16_bf16 v[0:15], v[204:207], v[234:237], v[0:15]
	s_waitcnt vmcnt(6)
	ds_write_b128 v177, v[148:151] offset:10240
	s_waitcnt lgkmcnt(9)
	v_mfma_f32_32x32x16_bf16 v[112:127], v[208:211], v[238:241], v[112:127]
	s_waitcnt vmcnt(5)
	ds_write_b128 v177, v[152:155] offset:12288
	v_mfma_f32_32x32x16_bf16 v[48:63], v[212:215], v[238:241], v[48:63]
	s_waitcnt vmcnt(4)
	ds_write_b128 v177, v[156:159] offset:14336
	s_waitcnt lgkmcnt(9)
	v_mfma_f32_32x32x16_bf16 v[96:111], v[208:211], v[242:245], v[96:111]
	s_waitcnt vmcnt(3)
	ds_write_b128 v177, v[160:163] offset:16384
	v_mfma_f32_32x32x16_bf16 v[32:47], v[212:215], v[242:245], v[32:47]
	s_waitcnt vmcnt(2)
	ds_write_b128 v177, v[164:167] offset:18432
	s_waitcnt lgkmcnt(9)
	v_mfma_f32_32x32x16_bf16 v[80:95], v[208:211], v[246:249], v[80:95]
	s_waitcnt vmcnt(1)
	ds_write_b128 v177, v[168:171] offset:20480
	v_mfma_f32_32x32x16_bf16 v[16:31], v[212:215], v[246:249], v[16:31]
	s_waitcnt vmcnt(0)
	ds_write_b128 v177, v[172:175] offset:22528
	s_waitcnt lgkmcnt(9)
	v_mfma_f32_32x32x16_bf16 v[64:79], v[208:211], v[192:195], v[64:79]
	v_mfma_f32_32x32x16_bf16 v[0:15], v[212:215], v[192:195], v[0:15]
	s_add_u32 s42, s42, 0x80
	s_addc_u32 s43, s43, 0
	s_add_u32 s44, s44, 0x80
	s_addc_u32 s45, s45, 0
	s_sub_i32 s36, s36, 0x6000
	s_cmp_lt_i32 s36, 0
	s_cselect_b32 s38, 0x12000, 0
	s_add_i32 s36, s36, s38
	s_sub_i32 s37, s37, 0x6000
	s_cmp_lt_i32 s37, 0
	s_cselect_b32 s38, 0x12000, 0
	s_add_i32 s37, s37, s38
	v_subrev_u32_e32 v196, 0x6000, v177
	v_add_u32_e32 v198, 0xc000, v177
	v_min_u32_e32 v177, v196, v198
	s_add_i32 s1, s1, 1
	s_cmp_lt_u32 s1, 15
	s_waitcnt lgkmcnt(0)
	s_barrier
	s_cbranch_scc1 .Lg5_loop
	v_add_u32_e32 v190, s36, v186
	v_add_u32_e32 v191, s36, v187
	v_add_u32_e32 v250, s36, v188
	v_add_u32_e32 v251, s36, v189
	ds_read_b128 v[200:203], v190
	ds_read_b128 v[204:207], v190 offset:2048
	ds_read_b128 v[222:225], v250
	ds_read_b128 v[226:229], v250 offset:2048
	ds_read_b128 v[230:233], v250 offset:4096
	ds_read_b128 v[234:237], v250 offset:6144
	s_waitcnt lgkmcnt(3)
	v_mfma_f32_32x32x16_bf16 v[112:127], v[200:203], v[222:225], v[112:127]
	ds_read_b128 v[208:211], v191
	v_mfma_f32_32x32x16_bf16 v[48:63], v[204:207], v[222:225], v[48:63]
	ds_read_b128 v[212:215], v191 offset:2048
	s_waitcnt lgkmcnt(4)
	v_mfma_f32_32x32x16_bf16 v[96:111], v[200:203], v[226:229], v[96:111]
	ds_read_b128 v[238:241], v251
	v_mfma_f32_32x32x16_bf16 v[32:47], v[204:207], v[226:229], v[32:47]
	ds_read_b128 v[242:245], v251 offset:2048
	s_waitcnt lgkmcnt(5)
	v_mfma_f32_32x32x16_bf16 v[80:95], v[200:203], v[230:233], v[80:95]
	ds_read_b128 v[246:249], v251 offset:4096
	v_mfma_f32_32x32x16_bf16 v[16:31], v[204:207], v[230:233], v[16:31]
	ds_read_b128 v[192:195], v251 offset:6144
	s_waitcnt lgkmcnt(6)
	v_mfma_f32_32x32x16_bf16 v[64:79], v[200:203], v[234:237], v[64:79]
	v_mfma_f32_32x32x16_bf16 v[0:15], v[204:207], v[234:237], v[0:15]
	v_xad_u32 v190, v186, 64, s37
	v_xad_u32 v250, v188, 64, s37
	s_waitcnt lgkmcnt(3)
	v_mfma_f32_32x32x16_bf16 v[112:127], v[208:211], v[238:241], v[112:127]
	ds_read_b128 v[200:203], v190
	v_mfma_f32_32x32x16_bf16 v[48:63], v[212:215], v[238:241], v[48:63]
	ds_read_b128 v[204:207], v190 offset:2048
	s_waitcnt lgkmcnt(4)
	v_mfma_f32_32x32x16_bf16 v[96:111], v[208:211], v[242:245], v[96:111]
	ds_read_b128 v[222:225], v250
	v_mfma_f32_32x32x16_bf16 v[32:47], v[212:215], v[242:245], v[32:47]
	ds_read_b128 v[226:229], v250 offset:2048
	s_waitcnt lgkmcnt(5)
	v_mfma_f32_32x32x16_bf16 v[80:95], v[208:211], v[246:249], v[80:95]
	ds_read_b128 v[230:233], v250 offset:4096
	v_mfma_f32_32x32x16_bf16 v[16:31], v[212:215], v[246:249], v[16:31]
	ds_read_b128 v[234:237], v250 offset:6144
	s_waitcnt lgkmcnt(6)
	v_mfma_f32_32x32x16_bf16 v[64:79], v[208:211], v[192:195], v[64:79]
	v_mfma_f32_32x32x16_bf16 v[0:15], v[212:215], v[192:195], v[0:15]
	v_xad_u32 v191, v187, 64, s37
	v_xad_u32 v251, v189, 64, s37
	s_waitcnt lgkmcnt(3)
	v_mfma_f32_32x32x16_bf16 v[112:127], v[200:203], v[222:225], v[112:127]
	ds_read_b128 v[208:211], v191
	v_mfma_f32_32x32x16_bf16 v[48:63], v[204:207], v[222:225], v[48:63]
	ds_read_b128 v[212:215], v191 offset:2048
	s_waitcnt lgkmcnt(4)
	v_mfma_f32_32x32x16_bf16 v[96:111], v[200:203], v[226:229], v[96:111]
	ds_read_b128 v[238:241], v251
	v_mfma_f32_32x32x16_bf16 v[32:47], v[204:207], v[226:229], v[32:47]
	ds_read_b128 v[242:245], v251 offset:2048
	s_waitcnt lgkmcnt(5)
	v_mfma_f32_32x32x16_bf16 v[80:95], v[200:203], v[230:233], v[80:95]
	ds_read_b128 v[246:249], v251 offset:4096
	v_mfma_f32_32x32x16_bf16 v[16:31], v[204:207], v[230:233], v[16:31]
	ds_read_b128 v[192:195], v251 offset:6144
	s_waitcnt lgkmcnt(6)
	v_mfma_f32_32x32x16_bf16 v[64:79], v[200:203], v[234:237], v[64:79]
	v_mfma_f32_32x32x16_bf16 v[0:15], v[204:207], v[234:237], v[0:15]
	s_waitcnt lgkmcnt(3)
	v_mfma_f32_32x32x16_bf16 v[112:127], v[208:211], v[238:241], v[112:127]
	v_mfma_f32_32x32x16_bf16 v[48:63], v[212:215], v[238:241], v[48:63]
	s_waitcnt lgkmcnt(2)
	v_mfma_f32_32x32x16_bf16 v[96:111], v[208:211], v[242:245], v[96:111]
	v_mfma_f32_32x32x16_bf16 v[32:47], v[212:215], v[242:245], v[32:47]
	s_waitcnt lgkmcnt(1)
	v_mfma_f32_32x32x16_bf16 v[80:95], v[208:211], v[246:249], v[80:95]
	v_mfma_f32_32x32x16_bf16 v[16:31], v[212:215], v[246:249], v[16:31]
	s_waitcnt lgkmcnt(0)
	v_mfma_f32_32x32x16_bf16 v[64:79], v[208:211], v[192:195], v[64:79]
	v_mfma_f32_32x32x16_bf16 v[0:15], v[212:215], v[192:195], v[0:15]
	s_setprio 0
	s_nop 7
	s_nop 7
	s_branch .LBB0_482

.Lg6_noraise:
.Lg6_loop:
	v_add_u32_e32 v190, s40, v186
	v_add_u32_e32 v191, s40, v187
	v_add_u32_e32 v250, s40, v188
	v_add_u32_e32 v251, s40, v189
	ds_read_b128 v[200:203], v190
	ds_read_b128 v[204:207], v190 offset:2048
	ds_read_b128 v[222:225], v250
	ds_read_b128 v[226:229], v250 offset:2048
	ds_read_b128 v[230:233], v250 offset:4096
	ds_read_b128 v[234:237], v250 offset:6144
	s_waitcnt lgkmcnt(3)
	v_mfma_f32_32x32x16_bf16 v[112:127], v[200:203], v[222:225], v[112:127]
	global_load_dwordx4 v[128:131], v176, s[28:29]
	ds_read_b128 v[208:211], v191
	v_mfma_f32_32x32x16_bf16 v[48:63], v[204:207], v[222:225], v[48:63]
	global_load_dwordx4 v[132:135], v177, s[28:29]
	ds_read_b128 v[212:215], v191 offset:2048
	s_waitcnt lgkmcnt(4)
	v_mfma_f32_32x32x16_bf16 v[96:111], v[200:203], v[226:229], v[96:111]
	ds_read_b128 v[238:241], v251
	v_mfma_f32_32x32x16_bf16 v[32:47], v[204:207], v[226:229], v[32:47]
	global_load_dwordx4 v[136:139], v178, s[28:29]
	ds_read_b128 v[242:245], v251 offset:2048
	s_waitcnt lgkmcnt(5)
	v_mfma_f32_32x32x16_bf16 v[80:95], v[200:203], v[230:233], v[80:95]
	global_load_dwordx4 v[140:143], v179, s[28:29]
	ds_read_b128 v[246:249], v251 offset:4096
	v_mfma_f32_32x32x16_bf16 v[16:31], v[204:207], v[230:233], v[16:31]
	global_load_dwordx4 v[144:147], v176, s[38:39]
	ds_read_b128 v[192:195], v251 offset:6144
	s_waitcnt lgkmcnt(6)
	v_mfma_f32_32x32x16_bf16 v[64:79], v[200:203], v[234:237], v[64:79]
	v_mfma_f32_32x32x16_bf16 v[0:15], v[204:207], v[234:237], v[0:15]
	global_load_dwordx4 v[148:151], v177, s[38:39]
	v_xad_u32 v190, v186, 64, s41
	v_xad_u32 v250, v188, 64, s41
	s_waitcnt lgkmcnt(3)
	v_mfma_f32_32x32x16_bf16 v[112:127], v[208:211], v[238:241], v[112:127]
	global_load_dwordx4 v[152:155], v178, s[38:39]
	ds_read_b128 v[200:203], v190
	v_mfma_f32_32x32x16_bf16 v[48:63], v[212:215], v[238:241], v[48:63]
	global_load_dwordx4 v[156:159], v179, s[38:39]
	ds_read_b128 v[204:207], v190 offset:2048
	s_waitcnt lgkmcnt(4)
	v_mfma_f32_32x32x16_bf16 v[96:111], v[208:211], v[242:245], v[96:111]
	ds_read_b128 v[222:225], v250
	v_mfma_f32_32x32x16_bf16 v[32:47], v[212:215], v[242:245], v[32:47]
	global_load_dwordx4 v[160:163], v180, s[38:39]
	ds_read_b128 v[226:229], v250 offset:2048
	s_waitcnt lgkmcnt(5)
	v_mfma_f32_32x32x16_bf16 v[80:95], v[208:211], v[246:249], v[80:95]
	global_load_dwordx4 v[164:167], v181, s[38:39]
	ds_read_b128 v[230:233], v250 offset:4096
	v_mfma_f32_32x32x16_bf16 v[16:31], v[212:215], v[246:249], v[16:31]
	global_load_dwordx4 v[168:171], v182, s[38:39]
	ds_read_b128 v[234:237], v250 offset:6144
	s_waitcnt lgkmcnt(6)
	v_mfma_f32_32x32x16_bf16 v[64:79], v[208:211], v[192:195], v[64:79]
	v_mfma_f32_32x32x16_bf16 v[0:15], v[212:215], v[192:195], v[0:15]
	global_load_dwordx4 v[172:175], v184, s[38:39]
	s_barrier
	v_xad_u32 v191, v187, 64, s41
	v_xad_u32 v251, v189, 64, s41
	s_waitcnt lgkmcnt(3)
	v_mfma_f32_32x32x16_bf16 v[112:127], v[200:203], v[222:225], v[112:127]
	ds_read_b128 v[208:211], v191
	v_mfma_f32_32x32x16_bf16 v[48:63], v[204:207], v[222:225], v[48:63]
	ds_read_b128 v[212:215], v191 offset:2048
	s_waitcnt lgkmcnt(4)
	v_mfma_f32_32x32x16_bf16 v[96:111], v[200:203], v[226:229], v[96:111]
	ds_read_b128 v[238:241], v251
	s_waitcnt vmcnt(11)
	ds_write_b128 v185, v[128:131]
	v_mfma_f32_32x32x16_bf16 v[32:47], v[204:207], v[226:229], v[32:47]
	ds_read_b128 v[242:245], v251 offset:2048
	s_waitcnt vmcnt(10)
	ds_write_b128 v185, v[132:135] offset:2048
	s_waitcnt lgkmcnt(7)
	v_mfma_f32_32x32x16_bf16 v[80:95], v[200:203], v[230:233], v[80:95]
	ds_read_b128 v[246:249], v251 offset:4096
	s_waitcnt vmcnt(9)
	ds_write_b128 v185, v[136:139] offset:4096
	v_mfma_f32_32x32x16_bf16 v[16:31], v[204:207], v[230:233], v[16:31]
	ds_read_b128 v[192:195], v251 offset:6144
	s_waitcnt vmcnt(8)
	ds_write_b128 v185, v[140:143] offset:6144
	s_waitcnt lgkmcnt(10)
	v_mfma_f32_32x32x16_bf16 v[64:79], v[200:203], v[234:237], v[64:79]
	s_waitcnt vmcnt(7)
	ds_write_b128 v185, v[144:147] offset:8192
	v_mfma_f32_32x32x16_bf16 v[0:15], v[204:207], v[234:237], v[0:15]
	s_waitcnt vmcnt(6)
	ds_write_b128 v185, v[148:151] offset:10240
	s_waitcnt lgkmcnt(9)
	v_mfma_f32_32x32x16_bf16 v[112:127], v[208:211], v[238:241], v[112:127]
	s_waitcnt vmcnt(5)
	ds_write_b128 v185, v[152:155] offset:12288
	v_mfma_f32_32x32x16_bf16 v[48:63], v[212:215], v[238:241], v[48:63]
	s_waitcnt vmcnt(4)
	ds_write_b128 v185, v[156:159] offset:14336
	s_waitcnt lgkmcnt(9)
	v_mfma_f32_32x32x16_bf16 v[96:111], v[208:211], v[242:245], v[96:111]
	s_waitcnt vmcnt(3)
	ds_write_b128 v185, v[160:163] offset:16384
	v_mfma_f32_32x32x16_bf16 v[32:47], v[212:215], v[242:245], v[32:47]
	s_waitcnt vmcnt(2)
	ds_write_b128 v185, v[164:167] offset:18432
	s_waitcnt lgkmcnt(9)
	v_mfma_f32_32x32x16_bf16 v[80:95], v[208:211], v[246:249], v[80:95]
	s_waitcnt vmcnt(1)
	ds_write_b128 v185, v[168:171] offset:20480
	v_mfma_f32_32x32x16_bf16 v[16:31], v[212:215], v[246:249], v[16:31]
	s_waitcnt vmcnt(0)
	ds_write_b128 v185, v[172:175] offset:22528
	s_waitcnt lgkmcnt(9)
	v_mfma_f32_32x32x16_bf16 v[64:79], v[208:211], v[192:195], v[64:79]
	v_mfma_f32_32x32x16_bf16 v[0:15], v[212:215], v[192:195], v[0:15]
	s_add_u32 s28, s28, 0x80
	s_addc_u32 s29, s29, 0
	s_add_u32 s38, s38, 0x80
	s_addc_u32 s39, s39, 0
	s_sub_i32 s40, s40, 0x6000
	s_cmp_lt_i32 s40, 0
	s_cselect_b32 s42, 0x12000, 0
	s_add_i32 s40, s40, s42
	s_sub_i32 s41, s41, 0x6000
	s_cmp_lt_i32 s41, 0
	s_cselect_b32 s42, 0x12000, 0
	s_add_i32 s41, s41, s42
	v_subrev_u32_e32 v196, 0x6000, v185
	v_add_u32_e32 v198, 0xc000, v185
	v_min_u32_e32 v185, v196, v198
	s_add_i32 s7, s7, 1
	s_cmp_lt_u32 s7, 63
	s_waitcnt lgkmcnt(0)
	s_barrier
	s_cbranch_scc1 .Lg6_loop
	v_add_u32_e32 v190, s40, v186
	v_add_u32_e32 v191, s40, v187
	v_add_u32_e32 v250, s40, v188
	v_add_u32_e32 v251, s40, v189
	ds_read_b128 v[200:203], v190
	ds_read_b128 v[204:207], v190 offset:2048
	ds_read_b128 v[222:225], v250
	ds_read_b128 v[226:229], v250 offset:2048
	ds_read_b128 v[230:233], v250 offset:4096
	ds_read_b128 v[234:237], v250 offset:6144
	s_waitcnt lgkmcnt(3)
	v_mfma_f32_32x32x16_bf16 v[112:127], v[200:203], v[222:225], v[112:127]
	ds_read_b128 v[208:211], v191
	v_mfma_f32_32x32x16_bf16 v[48:63], v[204:207], v[222:225], v[48:63]
	ds_read_b128 v[212:215], v191 offset:2048
	s_waitcnt lgkmcnt(4)
	v_mfma_f32_32x32x16_bf16 v[96:111], v[200:203], v[226:229], v[96:111]
	ds_read_b128 v[238:241], v251
	v_mfma_f32_32x32x16_bf16 v[32:47], v[204:207], v[226:229], v[32:47]
	ds_read_b128 v[242:245], v251 offset:2048
	s_waitcnt lgkmcnt(5)
	v_mfma_f32_32x32x16_bf16 v[80:95], v[200:203], v[230:233], v[80:95]
	ds_read_b128 v[246:249], v251 offset:4096
	v_mfma_f32_32x32x16_bf16 v[16:31], v[204:207], v[230:233], v[16:31]
	ds_read_b128 v[192:195], v251 offset:6144
	s_waitcnt lgkmcnt(6)
	v_mfma_f32_32x32x16_bf16 v[64:79], v[200:203], v[234:237], v[64:79]
	v_mfma_f32_32x32x16_bf16 v[0:15], v[204:207], v[234:237], v[0:15]
	v_xad_u32 v190, v186, 64, s41
	v_xad_u32 v250, v188, 64, s41
	s_waitcnt lgkmcnt(3)
	v_mfma_f32_32x32x16_bf16 v[112:127], v[208:211], v[238:241], v[112:127]
	ds_read_b128 v[200:203], v190
	v_mfma_f32_32x32x16_bf16 v[48:63], v[212:215], v[238:241], v[48:63]
	ds_read_b128 v[204:207], v190 offset:2048
	s_waitcnt lgkmcnt(4)
	v_mfma_f32_32x32x16_bf16 v[96:111], v[208:211], v[242:245], v[96:111]
	ds_read_b128 v[222:225], v250
	v_mfma_f32_32x32x16_bf16 v[32:47], v[212:215], v[242:245], v[32:47]
	ds_read_b128 v[226:229], v250 offset:2048
	s_waitcnt lgkmcnt(5)
	v_mfma_f32_32x32x16_bf16 v[80:95], v[208:211], v[246:249], v[80:95]
	ds_read_b128 v[230:233], v250 offset:4096
	v_mfma_f32_32x32x16_bf16 v[16:31], v[212:215], v[246:249], v[16:31]
	ds_read_b128 v[234:237], v250 offset:6144
	s_waitcnt lgkmcnt(6)
	v_mfma_f32_32x32x16_bf16 v[64:79], v[208:211], v[192:195], v[64:79]
	v_mfma_f32_32x32x16_bf16 v[0:15], v[212:215], v[192:195], v[0:15]
	v_xad_u32 v191, v187, 64, s41
	v_xad_u32 v251, v189, 64, s41
	s_waitcnt lgkmcnt(3)
	v_mfma_f32_32x32x16_bf16 v[112:127], v[200:203], v[222:225], v[112:127]
	ds_read_b128 v[208:211], v191
	v_mfma_f32_32x32x16_bf16 v[48:63], v[204:207], v[222:225], v[48:63]
	ds_read_b128 v[212:215], v191 offset:2048
	s_waitcnt lgkmcnt(4)
	v_mfma_f32_32x32x16_bf16 v[96:111], v[200:203], v[226:229], v[96:111]
	ds_read_b128 v[238:241], v251
	v_mfma_f32_32x32x16_bf16 v[32:47], v[204:207], v[226:229], v[32:47]
	ds_read_b128 v[242:245], v251 offset:2048
	s_waitcnt lgkmcnt(5)
	v_mfma_f32_32x32x16_bf16 v[80:95], v[200:203], v[230:233], v[80:95]
	ds_read_b128 v[246:249], v251 offset:4096
	v_mfma_f32_32x32x16_bf16 v[16:31], v[204:207], v[230:233], v[16:31]
	ds_read_b128 v[192:195], v251 offset:6144
	s_waitcnt lgkmcnt(6)
	v_mfma_f32_32x32x16_bf16 v[64:79], v[200:203], v[234:237], v[64:79]
	v_mfma_f32_32x32x16_bf16 v[0:15], v[204:207], v[234:237], v[0:15]
	s_waitcnt lgkmcnt(3)
	v_mfma_f32_32x32x16_bf16 v[112:127], v[208:211], v[238:241], v[112:127]
	v_mfma_f32_32x32x16_bf16 v[48:63], v[212:215], v[238:241], v[48:63]
	s_waitcnt lgkmcnt(2)
	v_mfma_f32_32x32x16_bf16 v[96:111], v[208:211], v[242:245], v[96:111]
	v_mfma_f32_32x32x16_bf16 v[32:47], v[212:215], v[242:245], v[32:47]
	s_waitcnt lgkmcnt(1)
	v_mfma_f32_32x32x16_bf16 v[80:95], v[208:211], v[246:249], v[80:95]
	v_mfma_f32_32x32x16_bf16 v[16:31], v[212:215], v[246:249], v[16:31]
	s_waitcnt lgkmcnt(0)
	v_mfma_f32_32x32x16_bf16 v[64:79], v[208:211], v[192:195], v[64:79]
	v_mfma_f32_32x32x16_bf16 v[0:15], v[212:215], v[192:195], v[0:15]
	s_setprio 0
	s_nop 7
	s_nop 7
